# FFN2-down GEMM epilogue: second residual load group issued together with the first into dead fragment registers (epilogue de-serialisation), copied into place after the first group's stores
# baseline (speedup 1.0000x reference)
; #define PG8_STAGE(bufoff, gbase, voff) do { _Pragma("unroll") for (int _i = 0; _i < 2; ++_i) \
;         __builtin_amdgcn_global_load_lds((const unsigned*)((const char*)(gbase) + (voff)[_i]), (LAS unsigned*)(lds + (bufoff) + ldsw + _i * 8192), 16, 0, 0); } while (0)
; #define PG8_LDA(dst, b, h) do { _Pragma("unroll") for (int m = 0; m < 4; ++m) _Pragma("unroll") for (int k = 0; k < 2; ++k) dst[m][k] = *(const LAS bf16x8*)(lds + PG8_SA(b, h) + aoff + m * 2048 + k * 1024); } while (0)
; #define PG8_LDB(dst, b, h) do { _Pragma("unroll") for (int n = 0; n < 2; ++n) _Pragma("unroll") for (int k = 0; k < 2; ++k) dst[n][k] = *(const LAS bf16x8*)(lds + PG8_SB(b, h) + boff + n * 2048 + k * 1024); } while (0)
; #define PG8_MMA(ai, bj, At, Bt) do { __builtin_amdgcn_s_setprio(1); _Pragma("unroll") for (int m = 0; m < 4; ++m) _Pragma("unroll") for (int n = 0; n < 2; ++n) _Pragma("unroll") for (int k = 0; k < 2; ++k) \
;         acc[ai][bj][m][n] = __builtin_amdgcn_mfma_f32_16x16x32_bf16(Bt[n][k], At[m][k], acc[ai][bj][m][n], 0, 0, 0); __builtin_amdgcn_s_setprio(0); } while (0)
; #define PG8_WAIT_V(n) asm volatile("s_waitcnt vmcnt(" #n ")" ::: "memory")
; #define PG8_WAIT_L(n) asm volatile("s_waitcnt lgkmcnt(" #n ")" ::: "memory")
; #define PG8_BAR __builtin_amdgcn_s_barrier()
; #define PG8_SCHED __builtin_amdgcn_sched_barrier(0)
; template <class Epi, class Sched>
; __device__ __forceinline__ void gemm_phase(LAS unsigned char* lds, const Gemm g, const Sched& S, const Epi& E) {
;     ...
;             PG8_LDB(B0, 0, 0); PG8_SCHED; PG8_LDA(At, 0, 0); PG8_STAGE(PG8_SA(1, 1), a1 + hstep, voffA);
;             PG8_WAIT_L(8); PG8_BAR; PG8_WAIT_L(0); PG8_MMA(0, 0, At, B0); PG8_BAR; PG8_SCHED;
;             PG8_LDB(B1, 0, 1); PG8_STAGE(PG8_SB(0, 0), b2, voffB);
;             PG8_BAR; PG8_WAIT_L(0); PG8_MMA(0, 1, At, B1); PG8_BAR;
;             PG8_LDA(At, 0, 1); PG8_STAGE(PG8_SA(0, 0), a2, voffA);
;             PG8_BAR; PG8_WAIT_L(0); PG8_MMA(1, 0, At, B0); PG8_BAR; PG8_SCHED;
;             PG8_STAGE(PG8_SB(0, 1), b2 + hstep, voffB);
;             PG8_WAIT_V(6); PG8_BAR; PG8_MMA(1, 1, At, B1); PG8_BAR;
.LBB0_1180:
	ds_read_b128 v[130:133], v156
	ds_read_b128 v[150:153], v156 offset:1024
	ds_read_b128 v[160:163], v156 offset:2048
	ds_read_b128 v[164:167], v156 offset:3072
	s_add_u32 s14, s12, 0xffea0080
	s_addc_u32 s15, s13, -1
	s_cmpk_eq_i32 s43, 0x54
	s_cselect_b32 s17, s7, s15
	s_cselect_b32 s16, s6, s14
	s_cselect_b32 s15, s1, s42
	s_cselect_b32 s14, s0, s41
	v_lshl_add_u64 v[200:201], s[12:13], 0, v[142:143]
	s_add_i32 m0, s25, 0xc000
	ds_read_b128 v[168:171], v157
	ds_read_b128 v[172:175], v157 offset:1024
	ds_read_b128 v[176:179], v157 offset:2048
	ds_read_b128 v[180:183], v157 offset:3072
	ds_read_b128 v[184:187], v157 offset:4096
	ds_read_b128 v[188:191], v157 offset:5120
	ds_read_b128 v[192:195], v157 offset:6144
	ds_read_b128 v[196:199], v157 offset:7168
	global_load_lds_dwordx4 v[200:201], off
	v_lshl_add_u64 v[200:201], s[12:13], 0, v[144:145]
	s_add_i32 m0, s25, 0xe000
	s_nop 0
	global_load_lds_dwordx4 v[200:201], off
	s_waitcnt lgkmcnt(8)
	s_barrier
	s_waitcnt lgkmcnt(0)
	s_setprio 1
	s_waitcnt lgkmcnt(0)
	v_mfma_f32_16x16x32_bf16 v[126:129], v[130:133], v[168:171], v[126:129]
	v_mfma_f32_16x16x32_bf16 v[122:125], v[160:163], v[168:171], v[122:125]
	v_mfma_f32_16x16x32_bf16 v[114:117], v[130:133], v[176:179], v[114:117]
	v_mfma_f32_16x16x32_bf16 v[106:109], v[160:163], v[176:179], v[106:109]
	v_mfma_f32_16x16x32_bf16 v[98:101], v[130:133], v[184:187], v[98:101]
	v_mfma_f32_16x16x32_bf16 v[90:93], v[160:163], v[184:187], v[90:93]
	v_mfma_f32_16x16x32_bf16 v[82:85], v[130:133], v[192:195], v[82:85]
	v_mfma_f32_16x16x32_bf16 v[74:77], v[160:163], v[192:195], v[74:77]
	v_mfma_f32_16x16x32_bf16 v[126:129], v[150:153], v[172:175], v[126:129]
	v_mfma_f32_16x16x32_bf16 v[122:125], v[164:167], v[172:175], v[122:125]
	v_mfma_f32_16x16x32_bf16 v[114:117], v[150:153], v[180:183], v[114:117]
	v_mfma_f32_16x16x32_bf16 v[106:109], v[164:167], v[180:183], v[106:109]
	v_mfma_f32_16x16x32_bf16 v[98:101], v[150:153], v[188:191], v[98:101]
	v_mfma_f32_16x16x32_bf16 v[90:93], v[164:167], v[188:191], v[90:93]
	v_mfma_f32_16x16x32_bf16 v[82:85], v[150:153], v[196:199], v[82:85]
	v_mfma_f32_16x16x32_bf16 v[74:77], v[164:167], v[196:199], v[74:77]
	s_setprio 0
	s_barrier
	s_add_i32 s44, s35, s23
	v_lshl_add_u64 v[204:205], s[14:15], 0, v[136:137]
	s_mov_b32 m0, s44
	ds_read_b128 v[200:203], v158
	ds_read_b128 v[208:211], v158 offset:1024
	ds_read_b128 v[212:215], v158 offset:2048
	ds_read_b128 v[216:219], v158 offset:3072
	global_load_lds_dwordx4 v[204:205], off
	v_lshl_add_u64 v[220:221], s[14:15], 0, v[140:141]
	s_add_i32 m0, s44, 0x2000
	s_nop 0
	global_load_lds_dwordx4 v[220:221], off
	s_barrier
	s_waitcnt lgkmcnt(0)
	s_setprio 1
	s_waitcnt lgkmcnt(0)
	v_mfma_f32_16x16x32_bf16 v[118:121], v[200:203], v[168:171], v[118:121]
	v_mfma_f32_16x16x32_bf16 v[110:113], v[212:215], v[168:171], v[110:113]
	v_mfma_f32_16x16x32_bf16 v[102:105], v[200:203], v[176:179], v[102:105]
	v_mfma_f32_16x16x32_bf16 v[94:97], v[212:215], v[176:179], v[94:97]
	v_mfma_f32_16x16x32_bf16 v[86:89], v[200:203], v[184:187], v[86:89]
	v_mfma_f32_16x16x32_bf16 v[78:81], v[212:215], v[184:187], v[78:81]
	v_mfma_f32_16x16x32_bf16 v[70:73], v[200:203], v[192:195], v[70:73]
	v_mfma_f32_16x16x32_bf16 v[66:69], v[212:215], v[192:195], v[66:69]
	v_mfma_f32_16x16x32_bf16 v[118:121], v[208:211], v[172:175], v[118:121]
	v_mfma_f32_16x16x32_bf16 v[110:113], v[216:219], v[172:175], v[110:113]
	v_mfma_f32_16x16x32_bf16 v[102:105], v[208:211], v[180:183], v[102:105]
	v_mfma_f32_16x16x32_bf16 v[94:97], v[216:219], v[180:183], v[94:97]
	v_mfma_f32_16x16x32_bf16 v[86:89], v[208:211], v[188:191], v[86:89]
	v_mfma_f32_16x16x32_bf16 v[78:81], v[216:219], v[188:191], v[78:81]
	v_mfma_f32_16x16x32_bf16 v[70:73], v[208:211], v[196:199], v[70:73]
	v_mfma_f32_16x16x32_bf16 v[66:69], v[216:219], v[196:199], v[66:69]
	s_setprio 0
	s_mov_b32 m0, s25
	v_lshl_add_u64 v[222:223], s[16:17], 0, v[134:135]
	s_barrier
	ds_read_b128 v[168:171], v157 offset:16384
	ds_read_b128 v[172:175], v157 offset:17408
	ds_read_b128 v[176:179], v157 offset:18432
	ds_read_b128 v[180:183], v157 offset:19456
	ds_read_b128 v[184:187], v157 offset:20480
	ds_read_b128 v[188:191], v157 offset:21504
	ds_read_b128 v[192:195], v157 offset:22528
	ds_read_b128 v[196:199], v157 offset:23552
	global_load_lds_dwordx4 v[222:223], off
	v_lshl_add_u64 v[224:225], s[16:17], 0, v[138:139]
	s_mov_b32 m0, s26
	s_nop 0
	global_load_lds_dwordx4 v[224:225], off
	s_barrier
	s_waitcnt lgkmcnt(0)
	s_setprio 1
	s_waitcnt lgkmcnt(0)
	v_mfma_f32_16x16x32_bf16 v[62:65], v[130:133], v[168:171], v[62:65]
	v_mfma_f32_16x16x32_bf16 v[58:61], v[160:163], v[168:171], v[58:61]
	v_mfma_f32_16x16x32_bf16 v[50:53], v[130:133], v[176:179], v[50:53]
	v_mfma_f32_16x16x32_bf16 v[42:45], v[160:163], v[176:179], v[42:45]
	v_mfma_f32_16x16x32_bf16 v[34:37], v[130:133], v[184:187], v[34:37]
	v_mfma_f32_16x16x32_bf16 v[26:29], v[160:163], v[184:187], v[26:29]
	v_mfma_f32_16x16x32_bf16 v[18:21], v[130:133], v[192:195], v[18:21]
	v_mfma_f32_16x16x32_bf16 v[10:13], v[160:163], v[192:195], v[10:13]
	v_mfma_f32_16x16x32_bf16 v[62:65], v[150:153], v[172:175], v[62:65]
	v_mfma_f32_16x16x32_bf16 v[58:61], v[164:167], v[172:175], v[58:61]
	v_mfma_f32_16x16x32_bf16 v[50:53], v[150:153], v[180:183], v[50:53]
	v_mfma_f32_16x16x32_bf16 v[42:45], v[164:167], v[180:183], v[42:45]
	v_mfma_f32_16x16x32_bf16 v[34:37], v[150:153], v[188:191], v[34:37]
	v_mfma_f32_16x16x32_bf16 v[26:29], v[164:167], v[188:191], v[26:29]
	v_mfma_f32_16x16x32_bf16 v[18:21], v[150:153], v[196:199], v[18:21]
	v_mfma_f32_16x16x32_bf16 v[10:13], v[164:167], v[196:199], v[10:13]
	s_setprio 0
	s_barrier
; #define PG8_STAGE(bufoff, gbase, voff) do { _Pragma("unroll") for (int _i = 0; _i < 2; ++_i) \
;         __builtin_amdgcn_global_load_lds((const unsigned*)((const char*)(gbase) + (voff)[_i]), (LAS unsigned*)(lds + (bufoff) + ldsw + _i * 8192), 16, 0, 0); } while (0)
; #define PG8_LDA(dst, b, h) do { _Pragma("unroll") for (int m = 0; m < 4; ++m) _Pragma("unroll") for (int k = 0; k < 2; ++k) dst[m][k] = *(const LAS bf16x8*)(lds + PG8_SA(b, h) + aoff + m * 2048 + k * 1024); } while (0)
; #define PG8_LDB(dst, b, h) do { _Pragma("unroll") for (int n = 0; n < 2; ++n) _Pragma("unroll") for (int k = 0; k < 2; ++k) dst[n][k] = *(const LAS bf16x8*)(lds + PG8_SB(b, h) + boff + n * 2048 + k * 1024); } while (0)
; #define PG8_MMA(ai, bj, At, Bt) do { __builtin_amdgcn_s_setprio(1); _Pragma("unroll") for (int m = 0; m < 4; ++m) _Pragma("unroll") for (int n = 0; n < 2; ++n) _Pragma("unroll") for (int k = 0; k < 2; ++k) \
;         acc[ai][bj][m][n] = __builtin_amdgcn_mfma_f32_16x16x32_bf16(Bt[n][k], At[m][k], acc[ai][bj][m][n], 0, 0, 0); __builtin_amdgcn_s_setprio(0); } while (0)
; #define PG8_WAIT_V(n) asm volatile("s_waitcnt vmcnt(" #n ")" ::: "memory")
; #define PG8_WAIT_L(n) asm volatile("s_waitcnt lgkmcnt(" #n ")" ::: "memory")
; #define PG8_BAR __builtin_amdgcn_s_barrier()
; #define PG8_SCHED __builtin_amdgcn_sched_barrier(0)
; template <class Epi, class Sched>
; __device__ __forceinline__ void gemm_phase(LAS unsigned char* lds, const Gemm g, const Sched& S, const Epi& E) {
;     ...
;             PG8_WAIT_V(6); PG8_BAR; PG8_MMA(1, 1, At, B1); PG8_BAR;
;             PG8_LDB(B0, 1, 0); PG8_SCHED; PG8_LDA(At, 1, 0); PG8_STAGE(PG8_SA(0, 1), a2 + hstep, voffA);
;             PG8_WAIT_L(8); PG8_BAR; PG8_WAIT_L(0); PG8_MMA(0, 0, At, B0); PG8_BAR; PG8_SCHED;
;             PG8_LDB(B1, 1, 1); PG8_STAGE(PG8_SB(1, 0), b3, voffB);
;             PG8_BAR; PG8_WAIT_L(0); PG8_MMA(0, 1, At, B1); PG8_BAR;
;             PG8_LDA(At, 1, 1); PG8_STAGE(PG8_SA(1, 0), a3, voffA);
;             PG8_BAR; PG8_WAIT_L(0); PG8_MMA(1, 0, At, B0); PG8_BAR; PG8_SCHED;
;             PG8_STAGE(PG8_SB(1, 1), b3 + hstep, voffB);
;             PG8_WAIT_V(6); PG8_BAR; PG8_MMA(1, 1, At, B1); PG8_BAR;
	s_add_u32 s44, s14, 0x160000
	s_addc_u32 s45, s15, 0
	s_add_i32 s46, s36, s23
	v_lshl_add_u64 v[130:131], s[44:45], 0, v[136:137]
	s_mov_b32 m0, s46
	s_nop 0
	global_load_lds_dwordx4 v[130:131], off
	v_lshl_add_u64 v[130:131], s[44:45], 0, v[140:141]
	s_add_i32 m0, s46, 0x2000
	s_nop 0
	global_load_lds_dwordx4 v[130:131], off
	s_waitcnt vmcnt(6)
	s_barrier
	s_setprio 1
	v_mfma_f32_16x16x32_bf16 v[54:57], v[200:203], v[168:171], v[54:57]
	v_mfma_f32_16x16x32_bf16 v[46:49], v[212:215], v[168:171], v[46:49]
	v_mfma_f32_16x16x32_bf16 v[38:41], v[200:203], v[176:179], v[38:41]
	v_mfma_f32_16x16x32_bf16 v[30:33], v[212:215], v[176:179], v[30:33]
	v_mfma_f32_16x16x32_bf16 v[22:25], v[200:203], v[184:187], v[22:25]
	v_mfma_f32_16x16x32_bf16 v[14:17], v[212:215], v[184:187], v[14:17]
	v_mfma_f32_16x16x32_bf16 v[6:9], v[200:203], v[192:195], v[6:9]
	v_mfma_f32_16x16x32_bf16 v[2:5], v[212:215], v[192:195], v[2:5]
	v_mfma_f32_16x16x32_bf16 v[54:57], v[208:211], v[172:175], v[54:57]
	v_mfma_f32_16x16x32_bf16 v[46:49], v[216:219], v[172:175], v[46:49]
	v_mfma_f32_16x16x32_bf16 v[38:41], v[208:211], v[180:183], v[38:41]
	v_mfma_f32_16x16x32_bf16 v[30:33], v[216:219], v[180:183], v[30:33]
	v_mfma_f32_16x16x32_bf16 v[22:25], v[208:211], v[188:191], v[22:25]
	v_mfma_f32_16x16x32_bf16 v[14:17], v[216:219], v[188:191], v[14:17]
	v_mfma_f32_16x16x32_bf16 v[6:9], v[208:211], v[196:199], v[6:9]
	v_mfma_f32_16x16x32_bf16 v[2:5], v[216:219], v[196:199], v[2:5]
	s_setprio 0
	s_add_i32 s44, 0, 0x18000
	v_add_u32_e32 v159, s44, v154
	s_barrier
	ds_read_b128 v[130:133], v159
	ds_read_b128 v[150:153], v159 offset:1024
	ds_read_b128 v[160:163], v159 offset:2048
	ds_read_b128 v[164:167], v159 offset:3072
	s_add_u32 s16, s16, 0x160000
	s_addc_u32 s17, s17, 0
	s_mov_b32 m0, s27
	v_lshl_add_u64 v[200:201], s[16:17], 0, v[134:135]
	ds_read_b128 v[168:171], v157 offset:32768
	ds_read_b128 v[172:175], v157 offset:33792
	ds_read_b128 v[176:179], v157 offset:34816
	ds_read_b128 v[180:183], v157 offset:35840
	ds_read_b128 v[184:187], v157 offset:36864
	ds_read_b128 v[188:191], v157 offset:37888
	ds_read_b128 v[192:195], v157 offset:38912
	ds_read_b128 v[196:199], v157 offset:39936
	global_load_lds_dwordx4 v[200:201], off
	v_lshl_add_u64 v[200:201], s[16:17], 0, v[138:139]
	s_mov_b32 m0, s28
	s_nop 0
	global_load_lds_dwordx4 v[200:201], off
	s_waitcnt lgkmcnt(8)
	s_barrier
	s_waitcnt lgkmcnt(0)
	s_setprio 1
	s_waitcnt lgkmcnt(0)
	v_mfma_f32_16x16x32_bf16 v[126:129], v[130:133], v[168:171], v[126:129]
	v_mfma_f32_16x16x32_bf16 v[122:125], v[160:163], v[168:171], v[122:125]
	v_mfma_f32_16x16x32_bf16 v[114:117], v[130:133], v[176:179], v[114:117]
	v_mfma_f32_16x16x32_bf16 v[106:109], v[160:163], v[176:179], v[106:109]
	v_mfma_f32_16x16x32_bf16 v[98:101], v[130:133], v[184:187], v[98:101]
	v_mfma_f32_16x16x32_bf16 v[90:93], v[160:163], v[184:187], v[90:93]
	v_mfma_f32_16x16x32_bf16 v[82:85], v[130:133], v[192:195], v[82:85]
	v_mfma_f32_16x16x32_bf16 v[74:77], v[160:163], v[192:195], v[74:77]
	v_mfma_f32_16x16x32_bf16 v[126:129], v[150:153], v[172:175], v[126:129]
	v_mfma_f32_16x16x32_bf16 v[122:125], v[164:167], v[172:175], v[122:125]
	v_mfma_f32_16x16x32_bf16 v[114:117], v[150:153], v[180:183], v[114:117]
	v_mfma_f32_16x16x32_bf16 v[106:109], v[164:167], v[180:183], v[106:109]
	v_mfma_f32_16x16x32_bf16 v[98:101], v[150:153], v[188:191], v[98:101]
	v_mfma_f32_16x16x32_bf16 v[90:93], v[164:167], v[188:191], v[90:93]
	v_mfma_f32_16x16x32_bf16 v[82:85], v[150:153], v[196:199], v[82:85]
	v_mfma_f32_16x16x32_bf16 v[74:77], v[164:167], v[196:199], v[74:77]
	s_setprio 0
	s_barrier
	s_add_i32 s16, 0, 0x1c000
	s_add_i32 s17, s44, s23
	v_add_u32_e32 v159, s16, v154
	v_lshl_add_u64 v[204:205], v[204:205], 0, s[10:11]
	s_mov_b32 m0, s17
	ds_read_b128 v[200:203], v159
	ds_read_b128 v[208:211], v159 offset:1024
	ds_read_b128 v[212:215], v159 offset:2048
	ds_read_b128 v[216:219], v159 offset:3072
	global_load_lds_dwordx4 v[204:205], off
	v_lshl_add_u64 v[204:205], v[220:221], 0, s[10:11]
	s_add_i32 m0, s17, 0x2000
	s_nop 0
	global_load_lds_dwordx4 v[204:205], off
	s_barrier
	s_waitcnt lgkmcnt(0)
	s_setprio 1
	s_waitcnt lgkmcnt(0)
	v_mfma_f32_16x16x32_bf16 v[118:121], v[200:203], v[168:171], v[118:121]
	v_mfma_f32_16x16x32_bf16 v[110:113], v[212:215], v[168:171], v[110:113]
	v_mfma_f32_16x16x32_bf16 v[102:105], v[200:203], v[176:179], v[102:105]
	v_mfma_f32_16x16x32_bf16 v[94:97], v[212:215], v[176:179], v[94:97]
	v_mfma_f32_16x16x32_bf16 v[86:89], v[200:203], v[184:187], v[86:89]
	v_mfma_f32_16x16x32_bf16 v[78:81], v[212:215], v[184:187], v[78:81]
	v_mfma_f32_16x16x32_bf16 v[70:73], v[200:203], v[192:195], v[70:73]
	v_mfma_f32_16x16x32_bf16 v[66:69], v[212:215], v[192:195], v[66:69]
	v_mfma_f32_16x16x32_bf16 v[118:121], v[208:211], v[172:175], v[118:121]
	v_mfma_f32_16x16x32_bf16 v[110:113], v[216:219], v[172:175], v[110:113]
	v_mfma_f32_16x16x32_bf16 v[102:105], v[208:211], v[180:183], v[102:105]
	v_mfma_f32_16x16x32_bf16 v[94:97], v[216:219], v[180:183], v[94:97]
	v_mfma_f32_16x16x32_bf16 v[86:89], v[208:211], v[188:191], v[86:89]
	v_mfma_f32_16x16x32_bf16 v[78:81], v[216:219], v[188:191], v[78:81]
	v_mfma_f32_16x16x32_bf16 v[70:73], v[208:211], v[196:199], v[70:73]
	v_mfma_f32_16x16x32_bf16 v[66:69], v[216:219], v[196:199], v[66:69]
	s_setprio 0
	s_mov_b32 m0, s31
	v_lshl_add_u64 v[204:205], v[222:223], 0, s[10:11]
	s_barrier
	ds_read_b128 v[168:171], v157 offset:49152
	ds_read_b128 v[172:175], v157 offset:50176
	ds_read_b128 v[176:179], v157 offset:51200
	ds_read_b128 v[180:183], v157 offset:52224
	ds_read_b128 v[184:187], v157 offset:53248
	ds_read_b128 v[188:191], v157 offset:54272
	ds_read_b128 v[192:195], v157 offset:55296
	ds_read_b128 v[196:199], v157 offset:56320
	global_load_lds_dwordx4 v[204:205], off
	v_lshl_add_u64 v[204:205], v[224:225], 0, s[10:11]
	s_mov_b32 m0, s33
	s_nop 0
	global_load_lds_dwordx4 v[204:205], off
	s_barrier
; #define PG8_STAGE(bufoff, gbase, voff) do { _Pragma("unroll") for (int _i = 0; _i < 2; ++_i) \
;         __builtin_amdgcn_global_load_lds((const unsigned*)((const char*)(gbase) + (voff)[_i]), (LAS unsigned*)(lds + (bufoff) + ldsw + _i * 8192), 16, 0, 0); } while (0)
; #define PG8_LDA(dst, b, h) do { _Pragma("unroll") for (int m = 0; m < 4; ++m) _Pragma("unroll") for (int k = 0; k < 2; ++k) dst[m][k] = *(const LAS bf16x8*)(lds + PG8_SA(b, h) + aoff + m * 2048 + k * 1024); } while (0)
; #define PG8_MMA(ai, bj, At, Bt) do { __builtin_amdgcn_s_setprio(1); _Pragma("unroll") for (int m = 0; m < 4; ++m) _Pragma("unroll") for (int n = 0; n < 2; ++n) _Pragma("unroll") for (int k = 0; k < 2; ++k) \
;         acc[ai][bj][m][n] = __builtin_amdgcn_mfma_f32_16x16x32_bf16(Bt[n][k], At[m][k], acc[ai][bj][m][n], 0, 0, 0); __builtin_amdgcn_s_setprio(0); } while (0)
; #define PG8_WAIT_V(n) asm volatile("s_waitcnt vmcnt(" #n ")" ::: "memory")
; #define PG8_WAIT_L(n) asm volatile("s_waitcnt lgkmcnt(" #n ")" ::: "memory")
; #define PG8_BAR __builtin_amdgcn_s_barrier()
; #define PG8_SCHED __builtin_amdgcn_sched_barrier(0)
; template <class Epi, class Sched>
; __device__ __forceinline__ void gemm_phase(LAS unsigned char* lds, const Gemm g, const Sched& S, const Epi& E) {
;     ...
;             PG8_BAR; PG8_WAIT_L(0); PG8_MMA(0, 1, At, B1); PG8_BAR;
;             PG8_LDA(At, 1, 1); PG8_STAGE(PG8_SA(1, 0), a3, voffA);
;             PG8_BAR; PG8_WAIT_L(0); PG8_MMA(1, 0, At, B0); PG8_BAR; PG8_SCHED;
;             PG8_STAGE(PG8_SB(1, 1), b3 + hstep, voffB);
;             PG8_WAIT_V(6); PG8_BAR; PG8_MMA(1, 1, At, B1); PG8_BAR;
;     DI void operator()(const f32x4 (&acc)[2][2][4][2], const pg8::Unit& u, int wr, int wc, int fr, int fq, int ui, LAS unsigned char* lds) const {
;         const int row0 = u.pm * 256 + wr * 64 + fr, col0 = u.pn * 256 + wc * 32 + 8 * fq;
; #pragma unroll
;         for (int ai = 0; ai < 2; ++ai) {
;             f32x4 bf0[4][2], bf1[4][2]; u32x4 bw[4][2];
; #pragma unroll
;             for (int m = 0; m < 4; ++m)
; #pragma unroll
;                 for (int bj = 0; bj < 2; ++bj) { const size_t off = (size_t)(row0 + ai * 128 + m * 16) * DM + col0 + bj * 128;
;                     if (MODE == 0) { bf0[m][bj] = *(const f32x4*)(basef + off); bf1[m][bj] = *(const f32x4*)(basef + off + 4); }
;                     else bw[m][bj] = *(const u32x4*)(baseb + off); }
	s_waitcnt lgkmcnt(0)
	s_setprio 1
	s_waitcnt lgkmcnt(0)
	v_mfma_f32_16x16x32_bf16 v[62:65], v[130:133], v[168:171], v[62:65]
	v_mfma_f32_16x16x32_bf16 v[58:61], v[160:163], v[168:171], v[58:61]
	v_mfma_f32_16x16x32_bf16 v[50:53], v[130:133], v[176:179], v[50:53]
	v_mfma_f32_16x16x32_bf16 v[42:45], v[160:163], v[176:179], v[42:45]
	v_mfma_f32_16x16x32_bf16 v[34:37], v[130:133], v[184:187], v[34:37]
	v_mfma_f32_16x16x32_bf16 v[26:29], v[160:163], v[184:187], v[26:29]
	v_mfma_f32_16x16x32_bf16 v[18:21], v[130:133], v[192:195], v[18:21]
	v_mfma_f32_16x16x32_bf16 v[10:13], v[160:163], v[192:195], v[10:13]
	v_mfma_f32_16x16x32_bf16 v[62:65], v[150:153], v[172:175], v[62:65]
	v_mfma_f32_16x16x32_bf16 v[58:61], v[164:167], v[172:175], v[58:61]
	v_mfma_f32_16x16x32_bf16 v[50:53], v[150:153], v[180:183], v[50:53]
	v_mfma_f32_16x16x32_bf16 v[42:45], v[164:167], v[180:183], v[42:45]
	v_mfma_f32_16x16x32_bf16 v[34:37], v[150:153], v[188:191], v[34:37]
	v_mfma_f32_16x16x32_bf16 v[26:29], v[164:167], v[188:191], v[26:29]
	v_mfma_f32_16x16x32_bf16 v[18:21], v[150:153], v[196:199], v[18:21]
	v_mfma_f32_16x16x32_bf16 v[10:13], v[164:167], v[196:199], v[10:13]
	s_setprio 0
	s_barrier
	s_add_u32 s14, s14, 0x160080
	s_addc_u32 s15, s15, 0
	s_add_i32 s16, s16, s23
	v_lshl_add_u64 v[130:131], s[14:15], 0, v[136:137]
	s_mov_b32 m0, s16
	s_nop 0
	global_load_lds_dwordx4 v[130:131], off
	v_lshl_add_u64 v[130:131], s[14:15], 0, v[140:141]
	s_add_i32 m0, s16, 0x2000
	s_nop 0
	global_load_lds_dwordx4 v[130:131], off
	s_waitcnt vmcnt(6)
	s_barrier
	s_setprio 1
	v_mfma_f32_16x16x32_bf16 v[54:57], v[200:203], v[168:171], v[54:57]
	v_mfma_f32_16x16x32_bf16 v[46:49], v[212:215], v[168:171], v[46:49]
	v_mfma_f32_16x16x32_bf16 v[38:41], v[200:203], v[176:179], v[38:41]
	v_mfma_f32_16x16x32_bf16 v[30:33], v[212:215], v[176:179], v[30:33]
	v_mfma_f32_16x16x32_bf16 v[22:25], v[200:203], v[184:187], v[22:25]
	v_mfma_f32_16x16x32_bf16 v[14:17], v[212:215], v[184:187], v[14:17]
	v_mfma_f32_16x16x32_bf16 v[6:9], v[200:203], v[192:195], v[6:9]
	v_mfma_f32_16x16x32_bf16 v[2:5], v[212:215], v[192:195], v[2:5]
	v_mfma_f32_16x16x32_bf16 v[54:57], v[208:211], v[172:175], v[54:57]
	v_mfma_f32_16x16x32_bf16 v[46:49], v[216:219], v[172:175], v[46:49]
	v_mfma_f32_16x16x32_bf16 v[38:41], v[208:211], v[180:183], v[38:41]
	v_mfma_f32_16x16x32_bf16 v[30:33], v[216:219], v[180:183], v[30:33]
	v_mfma_f32_16x16x32_bf16 v[22:25], v[208:211], v[188:191], v[22:25]
	v_mfma_f32_16x16x32_bf16 v[14:17], v[216:219], v[188:191], v[14:17]
	v_mfma_f32_16x16x32_bf16 v[6:9], v[208:211], v[196:199], v[6:9]
	v_mfma_f32_16x16x32_bf16 v[2:5], v[216:219], v[196:199], v[2:5]
	s_setprio 0
	s_add_i32 s43, s43, 2
	s_add_u32 s12, s12, 0x100
	s_addc_u32 s13, s13, 0
	s_add_u32 s41, s41, 0x100
	s_addc_u32 s42, s42, 0
	s_cmpk_gt_u32 s43, 0x55
	s_barrier
	s_cbranch_scc0 .LBB0_1180
	v_lshl_add_u32 v152, s39, 8, v1
	v_lshl_or_b32 v188, s40, 8, v155
	v_ashrrev_i32_e32 v189, 31, v188
	v_ashrrev_i32_e32 v153, 31, v152
	v_lshl_add_u64 v[150:151], v[188:189], 1, s[8:9]
	v_lshlrev_b64 v[130:131], 12, v[152:153]
	v_or_b32_e32 v190, 16, v152
	v_lshl_add_u64 v[130:131], v[150:151], 0, v[130:131]
	v_ashrrev_i32_e32 v191, 31, v190
	global_load_dwordx4 v[160:163], v[130:131], off
	global_load_dwordx4 v[164:167], v[130:131], off offset:256
	v_lshlrev_b64 v[130:131], 12, v[190:191]
	v_or_b32_e32 v192, 32, v152
	v_lshl_add_u64 v[130:131], v[150:151], 0, v[130:131]
	v_ashrrev_i32_e32 v193, 31, v192
	global_load_dwordx4 v[168:171], v[130:131], off
	global_load_dwordx4 v[172:175], v[130:131], off offset:256
	v_lshlrev_b64 v[130:131], 12, v[192:193]
	v_or_b32_e32 v194, 48, v152
	v_lshl_add_u64 v[130:131], v[150:151], 0, v[130:131]
	v_ashrrev_i32_e32 v195, 31, v194
	global_load_dwordx4 v[176:179], v[130:131], off
	global_load_dwordx4 v[180:183], v[130:131], off offset:256
	v_lshlrev_b64 v[130:131], 12, v[194:195]
	v_lshl_add_u64 v[130:131], v[150:151], 0, v[130:131]
	global_load_dwordx4 v[184:187], v[130:131], off
	s_nop 0
	global_load_dwordx4 v[130:133], v[130:131], off offset:256
	v_add_u32_e32 v200, 0x80, v152
	v_ashrrev_i32_e32 v201, 31, v200
	v_lshlrev_b64 v[200:201], 12, v[200:201]
	v_lshl_add_u64 v[200:201], v[150:151], 0, v[200:201]
	global_load_dwordx4 v[208:211], v[200:201], off
	global_load_dwordx4 v[212:215], v[200:201], off offset:256
	v_add_u32_e32 v200, 0x90, v152
	v_ashrrev_i32_e32 v201, 31, v200
	v_lshlrev_b64 v[200:201], 12, v[200:201]
	v_lshl_add_u64 v[200:201], v[150:151], 0, v[200:201]
	global_load_dwordx4 v[216:219], v[200:201], off
	global_load_dwordx4 v[220:223], v[200:201], off offset:256
	v_add_u32_e32 v200, 0xa0, v152
	v_ashrrev_i32_e32 v201, 31, v200
	v_lshlrev_b64 v[200:201], 12, v[200:201]
	v_lshl_add_u64 v[200:201], v[150:151], 0, v[200:201]
	global_load_dwordx4 v[224:227], v[200:201], off
	global_load_dwordx4 v[228:231], v[200:201], off offset:256
	v_add_u32_e32 v200, 0xb0, v152
	v_ashrrev_i32_e32 v201, 31, v200
	v_lshlrev_b64 v[200:201], 12, v[200:201]
	v_lshl_add_u64 v[200:201], v[150:151], 0, v[200:201]
	global_load_dwordx4 v[232:235], v[200:201], off
	global_load_dwordx4 v[236:239], v[200:201], off offset:256
	s_waitcnt vmcnt(8)
; DI unsigned pk2(float a, float b) { f32x2_t v = {a, b}; return __builtin_bit_cast(unsigned, __builtin_convertvector(v, bf16x2_t)); }
; DI float bflo(unsigned w) { return __uint_as_float(w << 16); }
; DI float bfhi(unsigned w) { return __uint_as_float(w & 0xffff0000u); }
;     DI void operator()(const f32x4 (&acc)[2][2][4][2], const pg8::Unit& u, int wr, int wc, int fr, int fq, int ui, LAS unsigned char* lds) const {
;     ...
;             for (int m = 0; m < 4; ++m) { const int row = row0 + ai * 128 + m * 16; const size_t off = (size_t)row * DM + col0; float rsum = 0.f;
; #pragma unroll
;                 for (int bj = 0; bj < 2; ++bj) {
;                     f32x4 b0, b1;
;                     if (MODE == 0) { b0 = bf0[m][bj]; b1 = bf1[m][bj]; }
;                     else { const u32x4 w = bw[m][bj]; b0 = (f32x4){bflo(w.x), bfhi(w.x), bflo(w.y), bfhi(w.y)}; b1 = (f32x4){bflo(w.z), bfhi(w.z), bflo(w.w), bfhi(w.w)}; }
;                     const f32x4 v0 = b0 + acc[ai][bj][m][0] * scale, v1 = b1 + acc[ai][bj][m][1] * scale;
;                     if (MODE == 2) { *(f32x4*)(outf + off + bj * 128) = v0; *(f32x4*)(outf + off + bj * 128 + 4) = v1; }
;                     else { rsum += (v0[0] * v0[0] + v0[1] * v0[1]) + (v0[2] * v0[2] + v0[3] * v0[3]) + (v1[0] * v1[0] + v1[1] * v1[1]) + (v1[2] * v1[2] + v1[3] * v1[3]);
;                         u32x4 w; w.x = pk2(v0[0], v0[1]); w.y = pk2(v0[2], v0[3]); w.z = pk2(v1[0], v1[1]); w.w = pk2(v1[2], v1[3]);
;                         *(u32x4*)(hb + off + bj * 128) = w; } }
	v_lshlrev_b32_e32 v196, 16, v160
	v_and_b32_e32 v197, 0xffff0000, v160
	v_lshlrev_b32_e32 v160, 16, v161
	v_and_b32_e32 v161, 0xffff0000, v161
	v_lshlrev_b32_e32 v198, 16, v162
	v_and_b32_e32 v199, 0xffff0000, v162
	v_lshlrev_b32_e32 v162, 16, v163
	v_and_b32_e32 v163, 0xffff0000, v163
	v_pk_fma_f32 v[128:129], v[128:129], 0.5, v[160:161] op_sel_hi:[1,0,1]
	v_pk_fma_f32 v[160:161], v[122:123], 0.5, v[198:199] op_sel_hi:[1,0,1]
	v_lshlrev_b64 v[122:123], 13, v[152:153]
	v_pk_fma_f32 v[162:163], v[124:125], 0.5, v[162:163] op_sel_hi:[1,0,1]
	v_lshl_add_u64 v[124:125], s[48:49], 0, v[122:123]
	v_lshlrev_b64 v[122:123], 2, v[188:189]
	v_pk_fma_f32 v[126:127], v[126:127], 0.5, v[196:197] op_sel_hi:[1,0,1]
	v_lshl_add_u64 v[124:125], v[124:125], 0, v[122:123]
	global_store_dwordx4 v[124:125], v[126:129], off
	global_store_dwordx4 v[124:125], v[160:163], off offset:16
	s_nop 0
	v_lshlrev_b32_e32 v126, 16, v164
	v_and_b32_e32 v127, 0xffff0000, v164
	v_lshlrev_b32_e32 v128, 16, v165
	v_and_b32_e32 v129, 0xffff0000, v165
	v_lshlrev_b32_e32 v160, 16, v166
	v_and_b32_e32 v161, 0xffff0000, v166
	v_lshlrev_b32_e32 v162, 16, v167
	v_and_b32_e32 v163, 0xffff0000, v167
	v_pk_fma_f32 v[120:121], v[120:121], 0.5, v[128:129] op_sel_hi:[1,0,1]
	v_pk_fma_f32 v[118:119], v[118:119], 0.5, v[126:127] op_sel_hi:[1,0,1]
	v_pk_fma_f32 v[110:111], v[110:111], 0.5, v[160:161] op_sel_hi:[1,0,1]
	v_pk_fma_f32 v[112:113], v[112:113], 0.5, v[162:163] op_sel_hi:[1,0,1]
	global_store_dwordx4 v[124:125], v[118:121], off offset:512
	global_store_dwordx4 v[124:125], v[110:113], off offset:528
	s_nop 0
	v_lshlrev_b32_e32 v118, 16, v170
	v_lshlrev_b32_e32 v110, 16, v168
	v_and_b32_e32 v111, 0xffff0000, v168
	v_pk_fma_f32 v[110:111], v[114:115], 0.5, v[110:111] op_sel_hi:[1,0,1]
	v_lshlrev_b64 v[114:115], 13, v[190:191]
	v_lshlrev_b32_e32 v112, 16, v169
	v_and_b32_e32 v113, 0xffff0000, v169
	v_and_b32_e32 v119, 0xffff0000, v170
	v_lshlrev_b32_e32 v120, 16, v171
	v_and_b32_e32 v121, 0xffff0000, v171
	v_lshl_add_u64 v[114:115], s[48:49], 0, v[114:115]
	v_pk_fma_f32 v[112:113], v[116:117], 0.5, v[112:113] op_sel_hi:[1,0,1]
	v_pk_fma_f32 v[108:109], v[108:109], 0.5, v[120:121] op_sel_hi:[1,0,1]
	v_pk_fma_f32 v[106:107], v[106:107], 0.5, v[118:119] op_sel_hi:[1,0,1]
	v_lshl_add_u64 v[114:115], v[114:115], 0, v[122:123]
	global_store_dwordx4 v[114:115], v[110:113], off
	global_store_dwordx4 v[114:115], v[106:109], off offset:16
	s_nop 0
	v_lshlrev_b32_e32 v110, 16, v174
	v_lshlrev_b32_e32 v106, 16, v172
	v_and_b32_e32 v107, 0xffff0000, v172
	v_lshlrev_b32_e32 v108, 16, v173
	v_and_b32_e32 v109, 0xffff0000, v173
	v_and_b32_e32 v111, 0xffff0000, v174
	v_lshlrev_b32_e32 v112, 16, v175
	v_and_b32_e32 v113, 0xffff0000, v175
	v_pk_fma_f32 v[104:105], v[104:105], 0.5, v[108:109] op_sel_hi:[1,0,1]
	v_pk_fma_f32 v[102:103], v[102:103], 0.5, v[106:107] op_sel_hi:[1,0,1]
	v_pk_fma_f32 v[94:95], v[94:95], 0.5, v[110:111] op_sel_hi:[1,0,1]
	v_pk_fma_f32 v[96:97], v[96:97], 0.5, v[112:113] op_sel_hi:[1,0,1]
	global_store_dwordx4 v[114:115], v[102:105], off offset:512
	global_store_dwordx4 v[114:115], v[94:97], off offset:528
	s_nop 0
	v_lshlrev_b32_e32 v102, 16, v178
	v_lshlrev_b32_e32 v94, 16, v176
	v_and_b32_e32 v95, 0xffff0000, v176
	v_pk_fma_f32 v[94:95], v[98:99], 0.5, v[94:95] op_sel_hi:[1,0,1]
	v_lshlrev_b64 v[98:99], 13, v[192:193]
	v_lshlrev_b32_e32 v96, 16, v177
	v_and_b32_e32 v97, 0xffff0000, v177
	v_and_b32_e32 v103, 0xffff0000, v178
	v_lshlrev_b32_e32 v104, 16, v179
	v_and_b32_e32 v105, 0xffff0000, v179
	v_lshl_add_u64 v[98:99], s[48:49], 0, v[98:99]
	v_pk_fma_f32 v[96:97], v[100:101], 0.5, v[96:97] op_sel_hi:[1,0,1]
	v_pk_fma_f32 v[92:93], v[92:93], 0.5, v[104:105] op_sel_hi:[1,0,1]
	v_pk_fma_f32 v[90:91], v[90:91], 0.5, v[102:103] op_sel_hi:[1,0,1]
	v_lshl_add_u64 v[98:99], v[98:99], 0, v[122:123]
	global_store_dwordx4 v[98:99], v[94:97], off
	global_store_dwordx4 v[98:99], v[90:93], off offset:16
	v_add_u32_e32 v100, 0x90, v152
	v_lshlrev_b32_e32 v94, 16, v182
	v_lshlrev_b32_e32 v90, 16, v180
	v_and_b32_e32 v91, 0xffff0000, v180
	v_lshlrev_b32_e32 v92, 16, v181
	v_and_b32_e32 v93, 0xffff0000, v181
	v_and_b32_e32 v95, 0xffff0000, v182
	v_lshlrev_b32_e32 v96, 16, v183
	v_and_b32_e32 v97, 0xffff0000, v183
	v_pk_fma_f32 v[88:89], v[88:89], 0.5, v[92:93] op_sel_hi:[1,0,1]
	v_pk_fma_f32 v[86:87], v[86:87], 0.5, v[90:91] op_sel_hi:[1,0,1]
	v_pk_fma_f32 v[78:79], v[78:79], 0.5, v[94:95] op_sel_hi:[1,0,1]
	v_pk_fma_f32 v[80:81], v[80:81], 0.5, v[96:97] op_sel_hi:[1,0,1]
	global_store_dwordx4 v[98:99], v[86:89], off offset:512
	global_store_dwordx4 v[98:99], v[78:81], off offset:528
	v_add_u32_e32 v98, 0x80, v152
	v_lshlrev_b32_e32 v86, 16, v186
	v_lshlrev_b32_e32 v78, 16, v184
	v_and_b32_e32 v79, 0xffff0000, v184
	v_pk_fma_f32 v[78:79], v[82:83], 0.5, v[78:79] op_sel_hi:[1,0,1]
	v_lshlrev_b64 v[82:83], 13, v[194:195]
	v_lshlrev_b32_e32 v80, 16, v185
	v_and_b32_e32 v81, 0xffff0000, v185
	v_and_b32_e32 v87, 0xffff0000, v186
	v_lshlrev_b32_e32 v88, 16, v187
	v_and_b32_e32 v89, 0xffff0000, v187
	v_lshl_add_u64 v[82:83], s[48:49], 0, v[82:83]
	v_pk_fma_f32 v[80:81], v[84:85], 0.5, v[80:81] op_sel_hi:[1,0,1]
	v_pk_fma_f32 v[76:77], v[76:77], 0.5, v[88:89] op_sel_hi:[1,0,1]
	v_pk_fma_f32 v[74:75], v[74:75], 0.5, v[86:87] op_sel_hi:[1,0,1]
	v_lshl_add_u64 v[82:83], v[82:83], 0, v[122:123]
	global_store_dwordx4 v[82:83], v[78:81], off
	global_store_dwordx4 v[82:83], v[74:77], off offset:16
	v_ashrrev_i32_e32 v99, 31, v98
	v_lshlrev_b32_e32 v78, 16, v132
	v_lshlrev_b32_e32 v74, 16, v130
	v_and_b32_e32 v75, 0xffff0000, v130
	v_lshlrev_b32_e32 v76, 16, v131
	v_and_b32_e32 v77, 0xffff0000, v131
	v_and_b32_e32 v79, 0xffff0000, v132
	v_lshlrev_b32_e32 v80, 16, v133
	v_and_b32_e32 v81, 0xffff0000, v133
	v_pk_fma_f32 v[72:73], v[72:73], 0.5, v[76:77] op_sel_hi:[1,0,1]
	v_pk_fma_f32 v[70:71], v[70:71], 0.5, v[74:75] op_sel_hi:[1,0,1]
	v_pk_fma_f32 v[66:67], v[66:67], 0.5, v[78:79] op_sel_hi:[1,0,1]
	v_pk_fma_f32 v[68:69], v[68:69], 0.5, v[80:81] op_sel_hi:[1,0,1]
	global_store_dwordx4 v[82:83], v[70:73], off offset:512
	global_store_dwordx4 v[82:83], v[66:69], off offset:528
	v_ashrrev_i32_e32 v101, 31, v100
	v_add_u32_e32 v102, 0xa0, v152
	v_ashrrev_i32_e32 v103, 31, v102
	v_add_u32_e32 v104, 0xb0, v152
	v_ashrrev_i32_e32 v105, 31, v104
	s_waitcnt vmcnt(16)
; DI unsigned pk2(float a, float b) { f32x2_t v = {a, b}; return __builtin_bit_cast(unsigned, __builtin_convertvector(v, bf16x2_t)); }
; DI float bflo(unsigned w) { return __uint_as_float(w << 16); }
; DI float bfhi(unsigned w) { return __uint_as_float(w & 0xffff0000u); }
; #define PG8_WAIT_V(n) asm volatile("s_waitcnt vmcnt(" #n ")" ::: "memory")
; #define PG8_BAR __builtin_amdgcn_s_barrier()
; template <class Epi, class Sched>
; __device__ __forceinline__ void gemm_phase(LAS unsigned char* lds, const Gemm g, const Sched& S, const Epi& E) {
;     ...
;         if (!has_next) break;
; #pragma unroll
;         for (int a = 0; a < 2; ++a)
; #pragma unroll
;             for (int b = 0; b < 2; ++b)
; #pragma unroll
;                 for (int m = 0; m < 4; ++m)
; #pragma unroll
;                     for (int n = 0; n < 2; ++n) acc[a][b][m][n] = (f32x4){0.f, 0.f, 0.f, 0.f};
;         cur = nxt; cA = nA; cB = nB; ++ui;
;     }
;     PG8_WAIT_V(0);
;     if (wr == 0) PG8_BAR;
;     PG8_BAR;
;     DI void operator()(const f32x4 (&acc)[2][2][4][2], const pg8::Unit& u, int wr, int wc, int fr, int fq, int ui, LAS unsigned char* lds) const {
;     ...
;             for (int m = 0; m < 4; ++m) { const int row = row0 + ai * 128 + m * 16; const size_t off = (size_t)row * DM + col0; float rsum = 0.f;
; #pragma unroll
;                 for (int bj = 0; bj < 2; ++bj) {
;                     f32x4 b0, b1;
;                     if (MODE == 0) { b0 = bf0[m][bj]; b1 = bf1[m][bj]; }
;                     else { const u32x4 w = bw[m][bj]; b0 = (f32x4){bflo(w.x), bfhi(w.x), bflo(w.y), bfhi(w.y)}; b1 = (f32x4){bflo(w.z), bfhi(w.z), bflo(w.w), bfhi(w.w)}; }
;                     const f32x4 v0 = b0 + acc[ai][bj][m][0] * scale, v1 = b1 + acc[ai][bj][m][1] * scale;
;                     if (MODE == 2) { *(f32x4*)(outf + off + bj * 128) = v0; *(f32x4*)(outf + off + bj * 128 + 4) = v1; }
;                     else { rsum += (v0[0] * v0[0] + v0[1] * v0[1]) + (v0[2] * v0[2] + v0[3] * v0[3]) + (v1[0] * v1[0] + v1[1] * v1[1]) + (v1[2] * v1[2] + v1[3] * v1[3]);
;                         u32x4 w; w.x = pk2(v0[0], v0[1]); w.y = pk2(v0[2], v0[3]); w.z = pk2(v1[0], v1[1]); w.w = pk2(v1[2], v1[3]);
;                         *(u32x4*)(hb + off + bj * 128) = w; } }
	v_mov_b32_e32 v70, v208
	v_mov_b32_e32 v71, v209
	v_mov_b32_e32 v72, v210
	v_mov_b32_e32 v73, v211
	v_mov_b32_e32 v74, v212
	v_mov_b32_e32 v75, v213
	v_mov_b32_e32 v76, v214
	v_mov_b32_e32 v77, v215
	v_mov_b32_e32 v78, v216
	v_mov_b32_e32 v79, v217
	v_mov_b32_e32 v80, v218
	v_mov_b32_e32 v81, v219
	v_mov_b32_e32 v82, v220
	v_mov_b32_e32 v83, v221
	v_mov_b32_e32 v84, v222
	v_mov_b32_e32 v85, v223
	v_mov_b32_e32 v86, v224
	v_mov_b32_e32 v87, v225
	v_mov_b32_e32 v88, v226
	v_mov_b32_e32 v89, v227
	v_mov_b32_e32 v90, v228
	v_mov_b32_e32 v91, v229
	v_mov_b32_e32 v92, v230
	v_mov_b32_e32 v93, v231
	v_mov_b32_e32 v94, v232
	v_mov_b32_e32 v95, v233
	v_mov_b32_e32 v96, v234
	v_mov_b32_e32 v97, v235
	v_mov_b32_e32 v66, v236
	v_mov_b32_e32 v67, v237
	v_mov_b32_e32 v68, v238
	v_mov_b32_e32 v69, v239
	v_lshlrev_b32_e32 v106, 16, v70
	v_and_b32_e32 v107, 0xffff0000, v70
	v_lshlrev_b32_e32 v70, 16, v71
	v_and_b32_e32 v71, 0xffff0000, v71
	v_pk_fma_f32 v[64:65], v[64:65], 0.5, v[70:71] op_sel_hi:[1,0,1]
	v_lshlrev_b64 v[70:71], 13, v[98:99]
	v_lshlrev_b32_e32 v108, 16, v72
	v_and_b32_e32 v109, 0xffff0000, v72
	v_lshlrev_b32_e32 v72, 16, v73
	v_and_b32_e32 v73, 0xffff0000, v73
	v_lshl_add_u64 v[70:71], s[48:49], 0, v[70:71]
	v_pk_fma_f32 v[62:63], v[62:63], 0.5, v[106:107] op_sel_hi:[1,0,1]
	v_pk_fma_f32 v[60:61], v[60:61], 0.5, v[72:73] op_sel_hi:[1,0,1]
	v_pk_fma_f32 v[58:59], v[58:59], 0.5, v[108:109] op_sel_hi:[1,0,1]
	v_lshl_add_u64 v[70:71], v[70:71], 0, v[122:123]
	global_store_dwordx4 v[70:71], v[62:65], off
	global_store_dwordx4 v[70:71], v[58:61], off offset:16
	s_and_b64 vcc, exec, s[4:5]
	v_lshlrev_b32_e32 v62, 16, v76
	v_lshlrev_b32_e32 v58, 16, v74
	v_and_b32_e32 v59, 0xffff0000, v74
	v_lshlrev_b32_e32 v60, 16, v75
	v_and_b32_e32 v61, 0xffff0000, v75
	v_and_b32_e32 v63, 0xffff0000, v76
	v_lshlrev_b32_e32 v64, 16, v77
	v_and_b32_e32 v65, 0xffff0000, v77
	v_pk_fma_f32 v[56:57], v[56:57], 0.5, v[60:61] op_sel_hi:[1,0,1]
	v_pk_fma_f32 v[54:55], v[54:55], 0.5, v[58:59] op_sel_hi:[1,0,1]
	v_pk_fma_f32 v[46:47], v[46:47], 0.5, v[62:63] op_sel_hi:[1,0,1]
	v_pk_fma_f32 v[48:49], v[48:49], 0.5, v[64:65] op_sel_hi:[1,0,1]
	global_store_dwordx4 v[70:71], v[54:57], off offset:512
	global_store_dwordx4 v[70:71], v[46:49], off offset:528
	s_mov_b32 s40, s37
	v_lshlrev_b32_e32 v54, 16, v80
	v_lshlrev_b32_e32 v46, 16, v78
	v_and_b32_e32 v47, 0xffff0000, v78
	v_pk_fma_f32 v[46:47], v[50:51], 0.5, v[46:47] op_sel_hi:[1,0,1]
	v_lshlrev_b64 v[50:51], 13, v[100:101]
	v_lshlrev_b32_e32 v48, 16, v79
	v_and_b32_e32 v49, 0xffff0000, v79
	v_and_b32_e32 v55, 0xffff0000, v80
	v_lshlrev_b32_e32 v56, 16, v81
	v_and_b32_e32 v57, 0xffff0000, v81
	v_lshl_add_u64 v[50:51], s[48:49], 0, v[50:51]
	v_pk_fma_f32 v[48:49], v[52:53], 0.5, v[48:49] op_sel_hi:[1,0,1]
	v_pk_fma_f32 v[44:45], v[44:45], 0.5, v[56:57] op_sel_hi:[1,0,1]
	v_pk_fma_f32 v[42:43], v[42:43], 0.5, v[54:55] op_sel_hi:[1,0,1]
	v_lshl_add_u64 v[50:51], v[50:51], 0, v[122:123]
	global_store_dwordx4 v[50:51], v[46:49], off
	global_store_dwordx4 v[50:51], v[42:45], off offset:16
	s_mov_b32 s39, s38
	v_lshlrev_b32_e32 v46, 16, v84
	v_lshlrev_b32_e32 v42, 16, v82
	v_and_b32_e32 v43, 0xffff0000, v82
	v_lshlrev_b32_e32 v44, 16, v83
	v_and_b32_e32 v45, 0xffff0000, v83
	v_and_b32_e32 v47, 0xffff0000, v84
	v_lshlrev_b32_e32 v48, 16, v85
	v_and_b32_e32 v49, 0xffff0000, v85
	v_pk_fma_f32 v[40:41], v[40:41], 0.5, v[44:45] op_sel_hi:[1,0,1]
	v_pk_fma_f32 v[38:39], v[38:39], 0.5, v[42:43] op_sel_hi:[1,0,1]
	v_pk_fma_f32 v[30:31], v[30:31], 0.5, v[46:47] op_sel_hi:[1,0,1]
	v_pk_fma_f32 v[32:33], v[32:33], 0.5, v[48:49] op_sel_hi:[1,0,1]
	global_store_dwordx4 v[50:51], v[38:41], off offset:512
	global_store_dwordx4 v[50:51], v[30:33], off offset:528
	s_mov_b64 s[14:15], s[0:1]
	v_lshlrev_b32_e32 v38, 16, v88
	v_lshlrev_b32_e32 v30, 16, v86
	v_and_b32_e32 v31, 0xffff0000, v86
	v_pk_fma_f32 v[30:31], v[34:35], 0.5, v[30:31] op_sel_hi:[1,0,1]
	v_lshlrev_b64 v[34:35], 13, v[102:103]
	v_lshlrev_b32_e32 v32, 16, v87
	v_and_b32_e32 v33, 0xffff0000, v87
	v_and_b32_e32 v39, 0xffff0000, v88
	v_lshlrev_b32_e32 v40, 16, v89
	v_and_b32_e32 v41, 0xffff0000, v89
	v_lshl_add_u64 v[34:35], s[48:49], 0, v[34:35]
	v_pk_fma_f32 v[32:33], v[36:37], 0.5, v[32:33] op_sel_hi:[1,0,1]
	v_pk_fma_f32 v[28:29], v[28:29], 0.5, v[40:41] op_sel_hi:[1,0,1]
	v_pk_fma_f32 v[26:27], v[26:27], 0.5, v[38:39] op_sel_hi:[1,0,1]
	v_lshl_add_u64 v[34:35], v[34:35], 0, v[122:123]
	global_store_dwordx4 v[34:35], v[30:33], off
	global_store_dwordx4 v[34:35], v[26:29], off offset:16
	s_mov_b64 s[12:13], s[6:7]
	v_lshlrev_b32_e32 v30, 16, v92
	v_lshlrev_b32_e32 v26, 16, v90
	v_and_b32_e32 v27, 0xffff0000, v90
	v_lshlrev_b32_e32 v28, 16, v91
	v_and_b32_e32 v29, 0xffff0000, v91
	v_and_b32_e32 v31, 0xffff0000, v92
	v_lshlrev_b32_e32 v32, 16, v93
	v_and_b32_e32 v33, 0xffff0000, v93
	v_pk_fma_f32 v[24:25], v[24:25], 0.5, v[28:29] op_sel_hi:[1,0,1]
	v_pk_fma_f32 v[22:23], v[22:23], 0.5, v[26:27] op_sel_hi:[1,0,1]
	v_pk_fma_f32 v[14:15], v[14:15], 0.5, v[30:31] op_sel_hi:[1,0,1]
	v_pk_fma_f32 v[16:17], v[16:17], 0.5, v[32:33] op_sel_hi:[1,0,1]
	global_store_dwordx4 v[34:35], v[22:25], off offset:512
	global_store_dwordx4 v[34:35], v[14:17], off offset:528
	s_nop 0
	v_lshlrev_b32_e32 v22, 16, v96
	v_lshlrev_b32_e32 v14, 16, v94
	v_and_b32_e32 v15, 0xffff0000, v94
	v_pk_fma_f32 v[14:15], v[18:19], 0.5, v[14:15] op_sel_hi:[1,0,1]
	v_lshlrev_b64 v[18:19], 13, v[104:105]
	v_lshlrev_b32_e32 v16, 16, v95
	v_and_b32_e32 v17, 0xffff0000, v95
	v_and_b32_e32 v23, 0xffff0000, v96
	v_lshlrev_b32_e32 v24, 16, v97
	v_and_b32_e32 v25, 0xffff0000, v97
	v_lshl_add_u64 v[18:19], s[48:49], 0, v[18:19]
	v_pk_fma_f32 v[16:17], v[20:21], 0.5, v[16:17] op_sel_hi:[1,0,1]
	v_pk_fma_f32 v[12:13], v[12:13], 0.5, v[24:25] op_sel_hi:[1,0,1]
	v_pk_fma_f32 v[10:11], v[10:11], 0.5, v[22:23] op_sel_hi:[1,0,1]
	v_lshl_add_u64 v[18:19], v[18:19], 0, v[122:123]
	global_store_dwordx4 v[18:19], v[14:17], off
	global_store_dwordx4 v[18:19], v[10:13], off offset:16
	s_nop 0
	v_lshlrev_b32_e32 v14, 16, v68
	v_lshlrev_b32_e32 v10, 16, v66
	v_and_b32_e32 v11, 0xffff0000, v66
	v_lshlrev_b32_e32 v12, 16, v67
	v_and_b32_e32 v13, 0xffff0000, v67
	v_and_b32_e32 v15, 0xffff0000, v68
	v_lshlrev_b32_e32 v16, 16, v69
	v_and_b32_e32 v17, 0xffff0000, v69
	v_pk_fma_f32 v[8:9], v[8:9], 0.5, v[12:13] op_sel_hi:[1,0,1]
	v_pk_fma_f32 v[6:7], v[6:7], 0.5, v[10:11] op_sel_hi:[1,0,1]
	v_pk_fma_f32 v[4:5], v[4:5], 0.5, v[16:17] op_sel_hi:[1,0,1]
	v_pk_fma_f32 v[2:3], v[2:3], 0.5, v[14:15] op_sel_hi:[1,0,1]
	global_store_dwordx4 v[18:19], v[6:9], off offset:512
	global_store_dwordx4 v[18:19], v[2:5], off offset:528
	s_cbranch_vccz .LBB0_1169
	s_waitcnt vmcnt(0)
	s_cmpk_gt_u32 s18, 0xff
	s_cbranch_scc1 .LBB0_1184
	s_barrier
